# MoBA K/V tiles double-buffered in LDS, one barrier per 128-key half
# speedup vs baseline: 1.0026x; 1.0026x over previous
; #define LAS __attribute__((address_space(3)))
; __device__ __forceinline__ void lds_barrier() { asm volatile("s_waitcnt lgkmcnt(0)" ::: "memory"); __builtin_amdgcn_s_barrier(); asm volatile("" ::: "memory"); }
; template <bool MOBA>
; __device__ __forceinline__ void attn_unit(LAS unsigned char* lds, const bf16_t* Qp, int ldq, const bf16_t* Kp, const bf16_t* Vp, int ldkv, bf16_t* Op, int ldo, int qt, const float* kmean, const float* relb, const int tid) {
;     ...
;     for (int hi = 0; hi < nhalf; ++hi) {
;         const int j = hi >> 1, kr0 = hi * 128;
;         lds_barrier();
; #pragma unroll
;         for (int i = 0; i < 4; ++i) { const int id = tid + 512 * i, r = id >> 4, c = id & 15;
;             *(LAS u32x4*)(lds + AT_KS + r * AT_PITCH + c * 16) = kreg[i]; *(LAS u32x4*)(lds + AT_VS + r * AT_VP + c * 16) = vreg[i]; }
;         lds_barrier();
.Ldb_exit:
	v_subrev_u32_e32 v194, s76, v194
	v_subrev_u32_e32 v183, s76, v183
	v_subrev_u32_e32 v184, s76, v184
	s_xor_b32 s77, s76, 0x15c00
	v_subrev_u32_e32 v182, s77, v182
	v_subrev_u32_e32 v190, s77, v190
	v_subrev_u32_e32 v191, s77, v191
	v_subrev_u32_e32 v192, s77, v192
	v_subrev_u32_e32 v193, s77, v193

; #define LAS __attribute__((address_space(3)))
; __device__ __forceinline__ void lds_barrier() { asm volatile("s_waitcnt lgkmcnt(0)" ::: "memory"); __builtin_amdgcn_s_barrier(); asm volatile("" ::: "memory"); }
; template <bool MOBA>
; __device__ __forceinline__ void attn_unit(LAS unsigned char* lds, const bf16_t* Qp, int ldq, const bf16_t* Kp, const bf16_t* Vp, int ldkv, bf16_t* Op, int ldo, int qt, const float* kmean, const float* relb, const int tid) {
;     ...
;         for (int s = 0; s < 4; ++s) qf[s] = *(const LAS bf16x8*)(lds + AT_KS + (w * 16 + l15) * AT_PITCH + (quad * 8 + 32 * s) * 2);
;         mysel = ((LAS unsigned*)(lds + AT_SEL))[w * 16 + l15];
;         { unsigned m = mysel; m |= __shfl_xor(m, 1); m |= __shfl_xor(m, 2); m |= __shfl_xor(m, 4); m |= __shfl_xor(m, 8); wave_mask = __builtin_amdgcn_readfirstlane(m); }
;     } else {
; #pragma unroll
;         for (int s = 0; s < 4; ++s) qf[s] = *(const bf16x8*)(Qp + (size_t)(w * 16 + l15) * ldq + quad * 8 + 32 * s);
;     }
;     f32x4 oacc[8]; float mrow = -INFINITY, lrow = 0.f;
; #pragma unroll
;     for (int n = 0; n < 8; ++n) oacc[n] = (f32x4){0.f, 0.f, 0.f, 0.f};
;     const int nhalf = MOBA ? own * 2 + (qt & 1) + 1 : 2;
;     const float sc2 = 0.08838834764831845f * L2E;
;     u32x4 kreg[4], vreg[4];
; #pragma unroll
;     for (int i = 0; i < 4; ++i) { const int id = tid + 512 * i, r = id >> 4, c = id & 15; kreg[i] = *(const u32x4*)(Kp + (size_t)r * ldkv + c * 8); vreg[i] = *(const u32x4*)(Vp + (size_t)r * ldkv + c * 8); }
; #pragma unroll 1
;     for (int hi = 0; hi < nhalf; ++hi) {
;         const int j = hi >> 1, kr0 = hi * 128;
;         lds_barrier();
; #pragma unroll
;         for (int i = 0; i < 4; ++i) { const int id = tid + 512 * i, r = id >> 4, c = id & 15;
;             *(LAS u32x4*)(lds + AT_KS + r * AT_PITCH + c * 16) = kreg[i]; *(LAS u32x4*)(lds + AT_VS + r * AT_VP + c * 16) = vreg[i]; }
;         lds_barrier();
;         if (hi + 1 < nhalf) {
; #pragma unroll
;             for (int i = 0; i < 4; ++i) { const int id = tid + 512 * i, r = id >> 4, c = id & 15; kreg[i] = *(const u32x4*)(Kp + (size_t)(kr0 + 128 + r) * ldkv + c * 8); vreg[i] = *(const u32x4*)(Vp + (size_t)(kr0 + 128 + r) * ldkv + c * 8); }
.LBB0_1175:
	s_or_b64 exec, exec, s[30:31]
	s_waitcnt lgkmcnt(0)
	s_barrier
	s_ashr_i32 s8, s55, 2
	s_and_b32 s28, s8, -16
	v_or_b32_e32 v139, s28, v170
	v_lshl_add_u32 v0, v139, 2, 0
	v_add_u32_e32 v0, 0x15800, v0
	ds_read_b32 v149, v0
	v_and_b32_e32 v1, 64, v195
	v_xor_b32_e32 v0, 1, v195
	v_add_u32_e32 v2, 64, v1
	v_cmp_lt_i32_e32 vcc, v0, v2
	v_xor_b32_e32 v1, 2, v195
	s_lshl_b32 s36, s53, 7
	v_cndmask_b32_e32 v0, v195, v0, vcc
	v_lshlrev_b32_e32 v0, 2, v0
	s_waitcnt lgkmcnt(0)
	ds_bpermute_b32 v0, v0, v149
	v_cmp_lt_i32_e32 vcc, v1, v2
	v_mov_b32_e32 v82, v115
	v_mov_b32_e32 v83, v115
	v_cndmask_b32_e32 v1, v195, v1, vcc
	s_waitcnt lgkmcnt(0)
	v_or_b32_e32 v0, v0, v149
	v_lshlrev_b32_e32 v1, 2, v1
	ds_bpermute_b32 v1, v1, v0
	s_add_i32 s37, s36, s28
	v_mov_b32_e32 v80, v115
	v_mov_b32_e32 v81, v115
	v_mov_b64_e32 v[86:87], v[82:83]
	s_waitcnt lgkmcnt(0)
	v_or_b32_e32 v3, v0, v1
	v_xor_b32_e32 v0, 4, v195
	v_cmp_lt_i32_e32 vcc, v0, v2
	v_mov_b64_e32 v[90:91], v[82:83]
	v_mov_b64_e32 v[94:95], v[82:83]
	v_cndmask_b32_e32 v0, v195, v0, vcc
	v_lshlrev_b32_e32 v0, 2, v0
	ds_bpermute_b32 v4, v0, v3
	v_mad_u64_u32 v[0:1], s[8:9], v139, s41, v[126:127]
	ds_read_b128 v[48:51], v0
	ds_read_b128 v[56:59], v0 offset:64
	ds_read_b128 v[60:63], v0 offset:128
	ds_read_b128 v[64:67], v0 offset:192
	v_mov_b64_e32 v[98:99], v[82:83]
	s_waitcnt lgkmcnt(4)
	v_or_b32_e32 v1, v3, v4
	v_xor_b32_e32 v3, 8, v195
	v_cmp_lt_i32_e32 vcc, v3, v2
	v_mov_b64_e32 v[102:103], v[82:83]
	v_mov_b64_e32 v[106:107], v[82:83]
	v_cndmask_b32_e32 v3, v195, v3, vcc
	v_lshlrev_b32_e32 v3, 2, v3
	ds_bpermute_b32 v3, v3, v1
	v_mov_b64_e32 v[110:111], v[82:83]
	s_mov_b32 s34, 0
	v_lshl_add_u64 v[158:159], v[150:151], 0, s[10:11]
	v_lshl_add_u64 v[160:161], v[152:153], 0, s[10:11]
	s_waitcnt lgkmcnt(0)
	v_or_b32_e32 v0, v1, v3
	v_lshl_add_u64 v[162:163], v[154:155], 0, s[10:11]
	v_readfirstlane_b32 s35, v0
	v_xor_b32_e32 v0, 16, v195
	v_cmp_lt_i32_e32 vcc, v0, v2
	v_lshl_add_u64 v[164:165], v[156:157], 0, s[10:11]
	v_add_u32_e32 v199, s37, v189
	v_cndmask_b32_e32 v0, v195, v0, vcc
	v_lshlrev_b32_e32 v197, 2, v0
	v_xor_b32_e32 v0, 32, v195
	v_cmp_lt_i32_e32 vcc, v0, v2
	v_mov_b32_e32 v201, 0xff800000
	v_mov_b32_e32 v200, 0
	v_cndmask_b32_e32 v0, v195, v0, vcc
	v_lshlrev_b32_e32 v198, 2, v0
	v_mov_b64_e32 v[84:85], v[80:81]
	v_mov_b64_e32 v[88:89], v[80:81]
	v_mov_b64_e32 v[92:93], v[80:81]
	v_mov_b64_e32 v[96:97], v[80:81]
	v_mov_b64_e32 v[100:101], v[80:81]
	v_mov_b64_e32 v[104:105], v[80:81]
	v_mov_b64_e32 v[108:109], v[80:81]
	s_mov_b32 s38, 0
	s_mov_b32 s73, 0x15c00
	s_mov_b32 s76, 0
	s_waitcnt lgkmcnt(0)
	s_barrier
	v_add_u32_e32 v0, v182, v172
	s_waitcnt vmcnt(7)
	ds_write_b128 v0, v[32:35]
	s_waitcnt vmcnt(6)
	ds_write_b128 v190, v[36:39] offset:34816
	v_add_u32_e32 v0, v182, v173
	s_waitcnt vmcnt(5)
	ds_write_b128 v0, v[40:43]
	s_waitcnt vmcnt(4)
	ds_write_b128 v191, v[44:47] offset:34816
	v_add_u32_e32 v0, v182, v174
	s_waitcnt vmcnt(3)
	ds_write_b128 v0, v[52:55]
	s_waitcnt vmcnt(2)
	ds_write_b128 v192, v[68:71] offset:34816
	v_add_u32_e32 v0, v182, v175
	s_waitcnt vmcnt(1)
	ds_write_b128 v0, v[72:75]
	s_waitcnt vmcnt(0)
	ds_write_b128 v193, v[76:79] offset:34816
	s_cmp_ge_u32 s38, s53
	s_cbranch_scc1 .Ldb_peel_noload
	v_lshl_add_u64 v[0:1], v[164:165], 0, s[14:15]
	v_add_co_u32_e32 v2, vcc, 0x95d0000, v0
	s_nop 1
	v_addc_co_u32_e32 v3, vcc, 0, v1, vcc
	v_add_co_u32_e32 v0, vcc, 0x95d1000, v0
	s_nop 1
	v_addc_co_u32_e32 v1, vcc, 0, v1, vcc
	global_load_dwordx4 v[32:35], v[2:3], off offset:2048
	global_load_dwordx4 v[36:39], v[0:1], off
	v_lshl_add_u64 v[0:1], v[162:163], 0, s[14:15]
	v_add_co_u32_e32 v2, vcc, 0x95d0000, v0
	s_nop 1
	v_addc_co_u32_e32 v3, vcc, 0, v1, vcc
	v_add_co_u32_e32 v0, vcc, 0x95d1000, v0
	s_nop 1
	v_addc_co_u32_e32 v1, vcc, 0, v1, vcc
	global_load_dwordx4 v[40:43], v[2:3], off offset:2048
	global_load_dwordx4 v[44:47], v[0:1], off
	v_lshl_add_u64 v[0:1], v[160:161], 0, s[14:15]
	v_add_co_u32_e32 v2, vcc, 0x95d0000, v0
	s_nop 1
	v_addc_co_u32_e32 v3, vcc, 0, v1, vcc
	v_add_co_u32_e32 v0, vcc, 0x95d1000, v0
	s_nop 1
	v_addc_co_u32_e32 v1, vcc, 0, v1, vcc
	global_load_dwordx4 v[52:55], v[2:3], off offset:2048
	global_load_dwordx4 v[68:71], v[0:1], off
	v_lshl_add_u64 v[0:1], v[158:159], 0, s[14:15]
	v_add_co_u32_e32 v2, vcc, 0x95d0000, v0
	s_nop 1
	v_addc_co_u32_e32 v3, vcc, 0, v1, vcc
	v_add_co_u32_e32 v0, vcc, 0x95d1000, v0
	s_nop 1
	v_addc_co_u32_e32 v1, vcc, 0, v1, vcc
	global_load_dwordx4 v[72:75], v[2:3], off offset:2048
	global_load_dwordx4 v[76:79], v[0:1], off
	v_lshl_add_u64 v[158:159], v[158:159], 0, s[24:25]
	v_lshl_add_u64 v[160:161], v[160:161], 0, s[24:25]
	v_lshl_add_u64 v[162:163], v[162:163], 0, s[24:25]
	v_lshl_add_u64 v[164:165], v[164:165], 0, s[24:25]
.Ldb_peel_noload:
	v_add_u32_e32 v182, s73, v182
	v_add_u32_e32 v190, s73, v190
	v_add_u32_e32 v191, s73, v191
	v_add_u32_e32 v192, s73, v192
	v_add_u32_e32 v193, s73, v193
	s_waitcnt lgkmcnt(0)
	s_barrier
.LBB0_1176:
	s_cmp_ge_u32 s38, s53
	s_cbranch_scc1 .LBB0_1178
	v_add_u32_e32 v0, v182, v172
	s_waitcnt vmcnt(7)
	ds_write_b128 v0, v[32:35]
	s_waitcnt vmcnt(6)
	ds_write_b128 v190, v[36:39] offset:34816
	v_add_u32_e32 v0, v182, v173
	s_waitcnt vmcnt(5)
	ds_write_b128 v0, v[40:43]
	s_waitcnt vmcnt(4)
	ds_write_b128 v191, v[44:47] offset:34816
	v_add_u32_e32 v0, v182, v174
	s_waitcnt vmcnt(3)
	ds_write_b128 v0, v[52:55]
	s_waitcnt vmcnt(2)
	ds_write_b128 v192, v[68:71] offset:34816
	v_add_u32_e32 v0, v182, v175
	s_waitcnt vmcnt(1)
	ds_write_b128 v0, v[72:75]
	s_waitcnt vmcnt(0)
	ds_write_b128 v193, v[76:79] offset:34816
	s_add_i32 s78, s38, 1
	s_cmp_ge_u32 s78, s53
	s_cbranch_scc1 .LBB0_1178
	v_lshl_add_u64 v[0:1], v[164:165], 0, s[14:15]
	v_add_co_u32_e32 v2, vcc, 0x95d0000, v0
	s_nop 1
	v_addc_co_u32_e32 v3, vcc, 0, v1, vcc
	v_add_co_u32_e32 v0, vcc, 0x95d1000, v0
	s_nop 1
	v_addc_co_u32_e32 v1, vcc, 0, v1, vcc
	global_load_dwordx4 v[32:35], v[2:3], off offset:2048
	global_load_dwordx4 v[36:39], v[0:1], off
	v_lshl_add_u64 v[0:1], v[162:163], 0, s[14:15]
	v_add_co_u32_e32 v2, vcc, 0x95d0000, v0
	s_nop 1
	v_addc_co_u32_e32 v3, vcc, 0, v1, vcc
	v_add_co_u32_e32 v0, vcc, 0x95d1000, v0
	s_nop 1
	v_addc_co_u32_e32 v1, vcc, 0, v1, vcc
	global_load_dwordx4 v[40:43], v[2:3], off offset:2048
	global_load_dwordx4 v[44:47], v[0:1], off
	v_lshl_add_u64 v[0:1], v[160:161], 0, s[14:15]
	v_add_co_u32_e32 v2, vcc, 0x95d0000, v0
	s_nop 1
	v_addc_co_u32_e32 v3, vcc, 0, v1, vcc
	v_add_co_u32_e32 v0, vcc, 0x95d1000, v0
	s_nop 1
	v_addc_co_u32_e32 v1, vcc, 0, v1, vcc
	global_load_dwordx4 v[52:55], v[2:3], off offset:2048
	global_load_dwordx4 v[68:71], v[0:1], off
	v_lshl_add_u64 v[0:1], v[158:159], 0, s[14:15]
	v_add_co_u32_e32 v2, vcc, 0x95d0000, v0
	s_nop 1
	v_addc_co_u32_e32 v3, vcc, 0, v1, vcc
	v_add_co_u32_e32 v0, vcc, 0x95d1000, v0
	s_nop 1
	v_addc_co_u32_e32 v1, vcc, 0, v1, vcc
	global_load_dwordx4 v[72:75], v[2:3], off offset:2048
	global_load_dwordx4 v[76:79], v[0:1], off

; #define LAS __attribute__((address_space(3)))
; __device__ __forceinline__ void lds_barrier() { asm volatile("s_waitcnt lgkmcnt(0)" ::: "memory"); __builtin_amdgcn_s_barrier(); asm volatile("" ::: "memory"); }
; template <bool MOBA>
; __device__ __forceinline__ void attn_unit(LAS unsigned char* lds, const bf16_t* Qp, int ldq, const bf16_t* Kp, const bf16_t* Vp, int ldkv, bf16_t* Op, int ldo, int qt, const float* kmean, const float* relb, const int tid) {
;     ...
;     for (int hi = 0; hi < nhalf; ++hi) {
;         const int j = hi >> 1, kr0 = hi * 128;
;         lds_barrier();
; #pragma unroll
;         for (int i = 0; i < 4; ++i) { const int id = tid + 512 * i, r = id >> 4, c = id & 15;
;             *(LAS u32x4*)(lds + AT_KS + r * AT_PITCH + c * 16) = kreg[i]; *(LAS u32x4*)(lds + AT_VS + r * AT_VP + c * 16) = vreg[i]; }
;         lds_barrier();
;         if (hi + 1 < nhalf) {
; #pragma unroll
;             for (int i = 0; i < 4; ++i) { const int id = tid + 512 * i, r = id >> 4, c = id & 15; kreg[i] = *(const u32x4*)(Kp + (size_t)(kr0 + 128 + r) * ldkv + c * 8); vreg[i] = *(const u32x4*)(Vp + (size_t)(kr0 + 128 + r) * ldkv + c * 8); }
.LBB0_1255:
	s_addk_i32 s34, 0xff80
	s_add_i32 s8, s36, s34
	s_add_i32 s38, s38, 1
	v_lshl_add_u64 v[158:159], v[158:159], 0, s[24:25]
	v_lshl_add_u64 v[160:161], v[160:161], 0, s[24:25]
	v_lshl_add_u64 v[162:163], v[162:163], 0, s[24:25]
	s_cmpk_lg_i32 s8, 0xff80
	v_lshl_add_u64 v[164:165], v[164:165], 0, s[24:25]
	s_cbranch_scc0 .Ldb_exit
	v_mov_b32_e32 v201, v216
	v_add_u32_e32 v194, s73, v194
	v_add_u32_e32 v183, s73, v183
	v_add_u32_e32 v184, s73, v184
	v_subrev_u32_e32 v182, s73, v182
	v_subrev_u32_e32 v190, s73, v190
	v_subrev_u32_e32 v191, s73, v191
	v_subrev_u32_e32 v192, s73, v192
	v_subrev_u32_e32 v193, s73, v193
	s_xor_b32 s76, s76, 0x15c00
	s_sub_i32 s73, 0, s73
	s_waitcnt lgkmcnt(0)
	s_barrier
	s_branch .LBB0_1176
